# v30 with the conv instruction stream at the other 8-byte phase (two s_nop, downstream placement unchanged mod 8)
# baseline (speedup 1.0000x reference)
.LBB0_501:
	s_or_b64 exec, exec, s[0:1]
	v_mov_b32_e32 v79, v184
	s_waitcnt lgkmcnt(0)
	s_barrier
	s_movk_i32 s0, 0x2000
	v_add_u32_e32 v0, s35, v79
	v_ashrrev_i32_e32 v80, 8, v0
	v_cmp_gt_i32_e32 vcc, s0, v80
	s_and_saveexec_b64 s[14:15], vcc
	s_cbranch_execz .LBB0_508
	s_nop 0

.LBB0_508:
	s_nop 0
	s_or_b64 exec, exec, s[14:15]
	v_ashrrev_i32_e32 v6, 6, v79
	v_readlane_b32 s0, v254, 42
	v_readlane_b32 s1, v254, 43
	s_nop 0
	v_add_u32_e32 v1, s0, v6
	s_movk_i32 s0, 0xa00
	v_cmp_gt_i32_e32 vcc, s0, v1
	s_and_saveexec_b64 s[48:49], vcc
	s_cbranch_execz .LBB0_519
	v_mbcnt_hi_u32_b32 v4, -1, v185
	v_and_b32_e32 v5, 64, v4
	v_add_u32_e32 v7, -1, v4
	v_cmp_lt_i32_e64 s[0:1], v7, v5
	s_add_u32 s68, s28, 0x145c0000
	s_addc_u32 s69, s29, 0
	v_cndmask_b32_e64 v7, v7, v4, s[0:1]
	v_lshlrev_b32_e32 v23, 2, v7
	v_add_u32_e32 v7, -2, v4
	v_cmp_lt_i32_e64 s[0:1], v7, v5
	s_movk_i32 s3, 0x600
	v_mov_b64_e32 v[8:9], s[28:29]
	v_cndmask_b32_e64 v7, v7, v4, s[0:1]
	v_lshlrev_b32_e32 v24, 2, v7
	v_add_u32_e32 v7, -4, v4
	v_cmp_lt_i32_e64 s[0:1], v7, v5
	v_and_b32_e32 v2, 63, v79
	v_lshlrev_b32_e32 v0, 1, v2
	v_cndmask_b32_e64 v7, v7, v4, s[0:1]
	v_lshlrev_b32_e32 v25, 2, v7
	v_add_u32_e32 v7, -8, v4
	v_cmp_lt_i32_e64 s[0:1], v7, v5
	v_mov_b32_e32 v3, 0
	v_or_b32_e32 v20, 1, v0
	v_cndmask_b32_e64 v7, v7, v4, s[0:1]
	v_lshlrev_b32_e32 v26, 2, v7
	v_add_u32_e32 v7, -16, v4
	v_cmp_lt_i32_e64 s[0:1], v7, v5
	v_xor_b32_e32 v21, 0x7f, v0
	v_xor_b32_e32 v22, 0x7e, v0
	v_cndmask_b32_e64 v7, v7, v4, s[0:1]
	v_lshlrev_b32_e32 v27, 2, v7
	v_subrev_u32_e32 v7, 32, v4
	v_cmp_lt_i32_e64 s[0:1], v7, v5
	v_cmp_eq_u32_e32 vcc, 0, v2
	v_cmp_gt_u32_e64 s[4:5], 2, v2
	v_cndmask_b32_e64 v4, v7, v4, s[0:1]
	v_readlane_b32 s0, v254, 42
	v_ashrrev_i32_e32 v7, 31, v6
	v_readlane_b32 s1, v254, 43
	s_mov_b32 s14, s0
	s_ashr_i32 s15, s0, 31
	v_writelane_b32 v254, s0, 42
	v_lshl_add_u64 v[6:7], v[6:7], 0, s[14:15]
	v_cmp_gt_u32_e64 s[6:7], 4, v2
	v_writelane_b32 v254, s1, 43
	v_mad_u64_u32 v[8:9], s[0:1], v6, s3, v[8:9]
	v_mad_i32_i24 v9, v7, s3, v9
	s_mov_b64 s[0:1], 0x14500400
	v_cmp_gt_u32_e64 s[8:9], 8, v2
	v_cmp_gt_u32_e64 s[10:11], 16, v2
	v_lshlrev_b32_e32 v28, 2, v4
	v_cmp_gt_u32_e64 s[12:13], 32, v2
	v_lshlrev_b32_e32 v4, 3, v2
	v_mov_b32_e32 v5, v3
	v_lshl_add_u64 v[6:7], v[8:9], 0, s[0:1]
	s_mul_hi_i32 s75, s34, 0x600
	s_mul_i32 s74, s34, 0x600
	s_mov_b64 s[76:77], 0
	s_movk_i32 s3, 0x1ff
	s_movk_i32 s16, 0x200
	v_mov_b32_e32 v29, 0x400
	v_mov_b32_e32 v30, 0x100
	v_mov_b32_e32 v31, 0x1000
	s_mov_b32 s17, 0x3fb8aa3b
	s_mov_b32 s18, 0xc2ce8ed0
	s_mov_b32 s19, 0x42b17218
	s_mov_b64 s[78:79], 0x200
	s_movk_i32 s22, 0x9ff
	s_waitcnt vmcnt(10)
	v_mov_b32_e32 v32, 0x7f800000
	v_mov_b32_e32 v33, 0xff800000
	s_branch .LBB0_511
